# mixer: no store drain (vmcnt 0) before each work-queue pop
# baseline (speedup 1.0000x reference)
.LBB0_78:
	v_mov_b32_e32 v0, v135
	s_barrier
	s_nop 0
	v_cmp_eq_u32_e32 vcc, 0, v0
	s_and_saveexec_b64 s[4:5], vcc
	s_cbranch_execz .LBB0_82
	s_mov_b64 s[16:17], exec
	v_mbcnt_lo_u32_b32 v0, s16, 0
	v_mbcnt_hi_u32_b32 v0, s17, v0
	v_cmp_eq_u32_e32 vcc, 0, v0
	s_and_saveexec_b64 s[12:13], vcc
	s_cbranch_execz .LBB0_81
	s_bcnt1_i32_b64 s16, s[16:17]
	v_mov_b32_e32 v1, s16
	global_atomic_add v1, v133, v1, s[10:11] sc0
